# G3 (OG rmsnorm*gate) loop software-pipelined: next trip's 16 loads issued before the current trip's 8 stores (store data parked in free VGPRs), counted waits re-derived
# speedup vs baseline: 1.0249x; 1.0129x over previous
; #define G3_LOAD(O0, O1, G0, G1_, m) do { O0 = *(const v4u*)(OG + (size_t)(m) * D + 16 * F.lane); O1 = *(const v4u*)(OG + (size_t)(m) * D + 16 * F.lane + 8); \
;             G0 = *(const v4u*)(GR + (size_t)(m) * D + 16 * F.lane); G1_ = *(const v4u*)(GR + (size_t)(m) * D + 16 * F.lane + 8); } while (0)
; template <int K> __device__ __forceinline__ void run_phase(const Args& args, LAS unsigned char* ldsp) {
;     ...
;         const int ms = MP + gw; const bool hasS = ms < M;
;         v4u so0, so1, sg0, sg1;
;         if (hasS) G3_LOAD(so0, so1, sg0, sg1, ms);
;         for (int m0 = 4 * gw; m0 < MP; m0 += 4 * NGW) {
;             v4u ov[4][2], gv4[4][2];
; #pragma unroll
;             for (int r = 0; r < 4; ++r) G3_LOAD(ov[r][0], ov[r][1], gv4[r][0], gv4[r][1], m0 + r);
; #pragma unroll
;             for (int r = 0; r < 4; ++r) G3_DONE(ov[r][0], ov[r][1], gv4[r][0], gv4[r][1], m0 + r);
.LBB0_1819:
	s_sub_u32 s100, 0, s14
	s_subb_u32 s101, 0, s15
	v_add_co_u32_e32 v42, vcc, 0xf3e7f000, v40
	v_lshl_add_u64 v[48:49], v[40:41], 0, s[18:19]
	s_nop 0
	v_addc_co_u32_e32 v43, vcc, -1, v41, vcc
	global_load_dwordx4 v[30:33], v[40:41], off offset:-4096
	global_load_dwordx4 v[34:37], v[40:41], off offset:-2048
	global_load_dwordx4 v[26:29], v[40:41], off offset:-2064
	global_load_dwordx4 v[18:21], v[40:41], off
	global_load_dwordx4 v[22:25], v[40:41], off offset:-16
	v_lshl_add_u64 v[50:51], v[40:41], 0, s[20:21]
	v_lshl_add_u64 v[52:53], v[40:41], 0, s[22:23]
	v_lshl_add_u64 v[46:47], v[40:41], 0, s[24:25]
	global_load_dwordx4 v[68:71], v[48:49], off offset:16
	global_load_dwordx4 v[78:81], v[50:51], off offset:16
	global_load_dwordx4 v[82:85], v[52:53], off offset:16
	v_add_co_u32_e32 v48, vcc, 0xfffff000, v40
	v_lshl_add_u64 v[44:45], v[40:41], 0, s[16:17]
	global_load_dwordx4 v[86:89], v[46:47], off offset:16
	global_load_dwordx4 v[90:93], v[42:43], off offset:-2064
	global_load_dwordx4 v[94:97], v[44:45], off offset:16
	v_addc_co_u32_e32 v49, vcc, -1, v41, vcc
	global_load_dwordx4 v[98:101], v[42:43], off offset:-16
	v_add_co_u32_e32 v44, vcc, s5, v40
	global_load_dwordx4 v[102:105], v[48:49], off offset:-2064
	global_load_dwordx4 v[106:109], v[48:49], off offset:-16
	v_addc_co_u32_e32 v45, vcc, -1, v41, vcc
	global_load_dwordx4 v[110:113], v[44:45], off offset:-2064
	global_load_dwordx4 v[114:117], v[44:45], off offset:-16
	s_add_i32 s10, s10, s12
	s_cmpk_gt_i32 s10, 0x7fff
	v_lshl_add_u64 v[40:41], v[40:41], 0, s[14:15]
	s_cselect_b32 s98, 1, 0
	s_waitcnt vmcnt(0)
.Lg3_loop:
	s_waitcnt vmcnt(23)
	v_lshlrev_b32_e32 v60, 16, v33
	v_and_b32_e32 v61, 0xffff0000, v33
	v_lshlrev_b32_e32 v62, 16, v32
	v_and_b32_e32 v63, 0xffff0000, v32
	v_lshlrev_b32_e32 v64, 16, v31
	v_and_b32_e32 v65, 0xffff0000, v31
	v_lshlrev_b32_e32 v66, 16, v30
	v_and_b32_e32 v67, 0xffff0000, v30
	s_waitcnt vmcnt(22)
	v_lshlrev_b32_e32 v30, 16, v37
	v_and_b32_e32 v31, 0xffff0000, v37
	v_lshlrev_b32_e32 v32, 16, v36
	v_and_b32_e32 v33, 0xffff0000, v36
	s_waitcnt vmcnt(14)
	v_lshlrev_b32_e32 v138, 16, v90
	v_and_b32_e32 v139, 0xffff0000, v90
	v_lshlrev_b32_e32 v36, 16, v35
	v_and_b32_e32 v37, 0xffff0000, v35
	s_waitcnt vmcnt(12)
	v_lshlrev_b32_e32 v150, 16, v98
	v_and_b32_e32 v151, 0xffff0000, v98
	v_lshlrev_b32_e32 v46, 16, v34
	v_and_b32_e32 v47, 0xffff0000, v34
	v_lshlrev_b32_e32 v34, 16, v29
	v_and_b32_e32 v35, 0xffff0000, v29
	v_lshlrev_b32_e32 v50, 16, v28
	v_and_b32_e32 v51, 0xffff0000, v28
	v_lshlrev_b32_e32 v28, 16, v19
	v_and_b32_e32 v29, 0xffff0000, v19
	v_lshlrev_b32_e32 v48, 16, v18
	v_and_b32_e32 v49, 0xffff0000, v18
	v_lshlrev_b32_e32 v18, 16, v25
	v_and_b32_e32 v19, 0xffff0000, v25
	v_lshlrev_b32_e32 v54, 16, v24
	v_and_b32_e32 v55, 0xffff0000, v24
	v_lshlrev_b32_e32 v24, 16, v23
	v_and_b32_e32 v25, 0xffff0000, v23
	v_lshlrev_b32_e32 v58, 16, v22
	v_and_b32_e32 v59, 0xffff0000, v22
	v_lshlrev_b32_e32 v118, 16, v71
	v_and_b32_e32 v119, 0xffff0000, v71
	v_lshlrev_b32_e32 v120, 16, v70
	v_and_b32_e32 v121, 0xffff0000, v70
	v_lshlrev_b32_e32 v122, 16, v69
	v_and_b32_e32 v123, 0xffff0000, v69
	v_lshlrev_b32_e32 v124, 16, v68
	v_and_b32_e32 v125, 0xffff0000, v68
	v_lshlrev_b32_e32 v126, 16, v81
	v_and_b32_e32 v127, 0xffff0000, v81
	v_lshlrev_b32_e32 v128, 16, v80
	v_and_b32_e32 v129, 0xffff0000, v80
	v_lshlrev_b32_e32 v80, 16, v79
	v_and_b32_e32 v81, 0xffff0000, v79
	v_lshlrev_b32_e32 v130, 16, v78
	v_and_b32_e32 v131, 0xffff0000, v78
	v_lshlrev_b32_e32 v68, 16, v85
	v_and_b32_e32 v69, 0xffff0000, v85
	v_lshlrev_b32_e32 v72, 16, v84
	v_and_b32_e32 v73, 0xffff0000, v84
	v_lshlrev_b32_e32 v132, 16, v83
	v_and_b32_e32 v133, 0xffff0000, v83
	v_lshlrev_b32_e32 v134, 16, v82
	v_and_b32_e32 v135, 0xffff0000, v82
	v_and_b32_e32 v22, 0xffff0000, v89
	v_lshlrev_b32_e32 v23, 16, v89
	v_lshlrev_b32_e32 v70, 16, v88
	v_and_b32_e32 v71, 0xffff0000, v88
	v_lshlrev_b32_e32 v88, 16, v87
	v_and_b32_e32 v89, 0xffff0000, v87
	v_lshlrev_b32_e32 v136, 16, v86
	v_and_b32_e32 v137, 0xffff0000, v86
	v_lshlrev_b32_e32 v78, 16, v97
	v_and_b32_e32 v79, 0xffff0000, v97
	v_lshlrev_b32_e32 v82, 16, v96
	v_and_b32_e32 v83, 0xffff0000, v96
	v_lshlrev_b32_e32 v84, 16, v95
	v_and_b32_e32 v85, 0xffff0000, v95
	v_lshlrev_b32_e32 v86, 16, v94
	v_and_b32_e32 v87, 0xffff0000, v94
	v_lshlrev_b32_e32 v94, 16, v93
	v_and_b32_e32 v95, 0xffff0000, v93
	v_lshlrev_b32_e32 v96, 16, v92
	v_and_b32_e32 v97, 0xffff0000, v92
	v_lshlrev_b32_e32 v92, 16, v91
	v_and_b32_e32 v93, 0xffff0000, v91
	v_lshlrev_b32_e32 v146, 16, v101
	v_and_b32_e32 v147, 0xffff0000, v101
	v_lshlrev_b32_e32 v148, 16, v100
	v_and_b32_e32 v149, 0xffff0000, v100
	v_lshlrev_b32_e32 v100, 16, v99
	v_and_b32_e32 v101, 0xffff0000, v99
	s_waitcnt vmcnt(11)
	v_lshlrev_b32_e32 v182, 16, v103
	v_and_b32_e32 v183, 0xffff0000, v103
	v_lshlrev_b32_e32 v186, 16, v102
	v_and_b32_e32 v187, 0xffff0000, v102
	v_pk_mul_f32 v[102:103], v[138:139], v[138:139]
	s_waitcnt vmcnt(10)
	v_lshlrev_b32_e32 v194, 16, v107
	v_and_b32_e32 v195, 0xffff0000, v107
	v_lshlrev_b32_e32 v198, 16, v106
	v_and_b32_e32 v199, 0xffff0000, v106
	v_pk_mul_f32 v[106:107], v[150:151], v[150:151]
	v_pk_mul_f32 v[184:185], v[92:93], v[92:93]
	v_pk_mul_f32 v[196:197], v[100:101], v[100:101]
	v_add_f32_e32 v167, v102, v103
	v_add_f32_e32 v206, v106, v107
	s_waitcnt vmcnt(9)
	v_lshlrev_b32_e32 v200, 16, v110
	v_and_b32_e32 v201, 0xffff0000, v110
	v_lshlrev_b32_e32 v102, 16, v113
	v_and_b32_e32 v103, 0xffff0000, v113
	v_lshlrev_b32_e32 v106, 16, v112
	v_and_b32_e32 v107, 0xffff0000, v112
	v_lshlrev_b32_e32 v112, 16, v111
	v_and_b32_e32 v113, 0xffff0000, v111
	s_waitcnt vmcnt(8)
	v_lshlrev_b32_e32 v204, 16, v114
	v_and_b32_e32 v205, 0xffff0000, v114
	v_add_f32_e32 v167, v184, v167
	v_add_f32_e32 v184, v196, v206
	v_pk_mul_f32 v[210:211], v[200:201], v[200:201]
	v_lshlrev_b32_e32 v176, 16, v105
	v_and_b32_e32 v177, 0xffff0000, v105
	v_lshlrev_b32_e32 v180, 16, v104
	v_and_b32_e32 v181, 0xffff0000, v104
	v_pk_mul_f32 v[104:105], v[96:97], v[96:97]
	v_lshlrev_b32_e32 v188, 16, v109
	v_and_b32_e32 v189, 0xffff0000, v109
	v_lshlrev_b32_e32 v192, 16, v108
	v_and_b32_e32 v193, 0xffff0000, v108
	v_pk_mul_f32 v[108:109], v[148:149], v[148:149]
	v_lshlrev_b32_e32 v110, 16, v117
	v_and_b32_e32 v111, 0xffff0000, v117
	v_lshlrev_b32_e32 v202, 16, v116
	v_and_b32_e32 v203, 0xffff0000, v116
	v_lshlrev_b32_e32 v116, 16, v115
	v_and_b32_e32 v117, 0xffff0000, v115
	v_pk_mul_f32 v[208:209], v[112:113], v[112:113]
	v_pk_mul_f32 v[218:219], v[204:205], v[204:205]
	v_add_f32_e32 v167, v185, v167
	v_add_f32_e32 v184, v197, v184
	v_add_f32_e32 v185, v210, v211
	v_pk_mul_f32 v[216:217], v[116:117], v[116:117]
	v_add_f32_e32 v196, v218, v219
	v_add_f32_e32 v104, v104, v167
	v_add_f32_e32 v108, v108, v184
	v_add_f32_e32 v167, v208, v185
	v_pk_mul_f32 v[178:179], v[94:95], v[94:95]
	v_pk_mul_f32 v[190:191], v[146:147], v[146:147]
	v_pk_mul_f32 v[206:207], v[106:107], v[106:107]
	v_add_f32_e32 v184, v216, v196
	v_add_f32_e32 v104, v105, v104
	v_add_f32_e32 v105, v109, v108
	v_add_f32_e32 v108, v209, v167
	v_pk_mul_f32 v[214:215], v[202:203], v[202:203]
	v_add_f32_e32 v109, v217, v184
	v_add_f32_e32 v104, v178, v104
	v_add_f32_e32 v105, v190, v105
	v_add_f32_e32 v108, v206, v108
	v_pk_mul_f32 v[144:145], v[130:131], v[130:131]
	v_pk_mul_f32 v[174:175], v[86:87], v[86:87]
	v_pk_mul_f32 v[114:115], v[102:103], v[102:103]
	v_add_f32_e32 v109, v214, v109
	v_add_f32_e32 v104, v179, v104
	v_add_f32_e32 v105, v191, v105
	v_add_f32_e32 v108, v207, v108
	v_pk_mul_f32 v[212:213], v[110:111], v[110:111]
	v_add_f32_e32 v109, v215, v109
	v_add_f32_e32 v104, v174, v104
	v_add_f32_e32 v105, v144, v105
	v_add_f32_e32 v108, v114, v108
	v_pk_mul_f32 v[142:143], v[80:81], v[80:81]
	v_pk_mul_f32 v[156:157], v[134:135], v[134:135]
	v_pk_mul_f32 v[172:173], v[84:85], v[84:85]
	v_add_f32_e32 v109, v212, v109
	v_add_f32_e32 v104, v175, v104
	v_add_f32_e32 v105, v145, v105
	v_add_f32_e32 v108, v115, v108
	v_pk_mul_f32 v[164:165], v[136:137], v[136:137]
	v_add_f32_e32 v109, v213, v109
	v_add_f32_e32 v104, v172, v104
	v_add_f32_e32 v105, v142, v105
	v_add_f32_e32 v108, v156, v108
	v_pk_mul_f32 v[140:141], v[128:129], v[128:129]
	v_pk_mul_f32 v[154:155], v[132:133], v[132:133]
	v_pk_mul_f32 v[170:171], v[82:83], v[82:83]
	v_add_f32_e32 v109, v164, v109
	v_add_f32_e32 v104, v173, v104
	v_add_f32_e32 v105, v143, v105
	v_add_f32_e32 v108, v157, v108
	v_pk_mul_f32 v[162:163], v[88:89], v[88:89]
	v_add_f32_e32 v109, v165, v109
	v_add_f32_e32 v104, v170, v104
	v_add_f32_e32 v105, v140, v105
	v_add_f32_e32 v108, v154, v108
	v_pk_mul_f32 v[90:91], v[126:127], v[126:127]
	v_pk_mul_f32 v[152:153], v[72:73], v[72:73]
	v_pk_mul_f32 v[168:169], v[78:79], v[78:79]
	v_add_f32_e32 v109, v162, v109
	v_add_f32_e32 v104, v171, v104
	v_add_f32_e32 v105, v141, v105
	v_add_f32_e32 v108, v155, v108
	v_pk_mul_f32 v[160:161], v[70:71], v[70:71]
	v_add_f32_e32 v109, v163, v109
	v_add_f32_e32 v104, v168, v104
	v_add_f32_e32 v90, v90, v105
	v_add_f32_e32 v105, v152, v108
	v_pk_mul_f32 v[98:99], v[68:69], v[68:69]
	v_add_f32_e32 v108, v160, v109
	v_add_f32_e32 v104, v169, v104
	v_add_f32_e32 v90, v91, v90
	v_add_f32_e32 v91, v153, v105
	v_pk_mul_f32 v[158:159], v[22:23], v[22:23]
	v_add_f32_e32 v105, v161, v108
	ds_bpermute_b32 v108, v74, v104
	ds_bpermute_b32 v109, v74, v90
	v_add_f32_e32 v91, v98, v91
	v_add_f32_e32 v98, v159, v105
	v_add_f32_e32 v91, v99, v91
	v_add_f32_e32 v98, v158, v98
	ds_bpermute_b32 v99, v74, v91
	ds_bpermute_b32 v105, v74, v98
	s_waitcnt lgkmcnt(3)
	v_add_f32_e32 v104, v104, v108
	s_waitcnt lgkmcnt(2)
	v_add_f32_e32 v90, v90, v109
	ds_bpermute_b32 v108, v75, v104
	ds_bpermute_b32 v109, v75, v90
	s_waitcnt lgkmcnt(3)
	v_add_f32_e32 v91, v91, v99
	s_waitcnt lgkmcnt(2)
	v_add_f32_e32 v98, v98, v105
	ds_bpermute_b32 v99, v75, v91
	ds_bpermute_b32 v105, v75, v98
	s_waitcnt lgkmcnt(3)
	v_add_f32_e32 v104, v104, v108
	s_waitcnt lgkmcnt(2)
	v_add_f32_e32 v90, v90, v109
	ds_bpermute_b32 v108, v76, v104
	ds_bpermute_b32 v109, v76, v90
	s_waitcnt lgkmcnt(3)
	v_add_f32_e32 v91, v91, v99
	s_waitcnt lgkmcnt(2)
	v_add_f32_e32 v98, v98, v105
	ds_bpermute_b32 v99, v76, v91
	ds_bpermute_b32 v105, v76, v98
	s_waitcnt lgkmcnt(3)
	v_add_f32_e32 v104, v104, v108
	s_waitcnt lgkmcnt(2)
	v_add_f32_e32 v90, v90, v109
	ds_bpermute_b32 v108, v77, v104
	ds_bpermute_b32 v109, v77, v90
	s_waitcnt lgkmcnt(3)
	v_add_f32_e32 v91, v91, v99
	s_waitcnt lgkmcnt(2)
	v_add_f32_e32 v99, v98, v105
	ds_bpermute_b32 v105, v77, v91
	ds_bpermute_b32 v114, v77, v99
	s_waitcnt lgkmcnt(3)
	v_add_f32_e32 v98, v104, v108
	s_waitcnt lgkmcnt(2)
	v_add_f32_e32 v90, v90, v109
	v_fmamk_f32 v98, v98, 0x3b800000, v39
	v_fmamk_f32 v104, v90, 0x3b800000, v39
	v_rsq_f32_e32 v90, v98
	v_rsq_f32_e32 v98, v104
	s_waitcnt lgkmcnt(1)
	v_add_f32_e32 v91, v91, v105
	s_waitcnt lgkmcnt(0)
	v_add_f32_e32 v99, v99, v114
	v_fmamk_f32 v91, v91, 0x3b800000, v39
	v_fmamk_f32 v99, v99, 0x3b800000, v39
	v_rsq_f32_e32 v104, v91
	v_rsq_f32_e32 v108, v99
	v_pk_mul_f32 v[114:115], v[90:91], v[138:139] op_sel_hi:[0,1]
	v_pk_mul_f32 v[92:93], v[90:91], v[92:93] op_sel_hi:[0,1]
	v_pk_mul_f32 v[96:97], v[90:91], v[96:97] op_sel_hi:[0,1]
	v_pk_mul_f32 v[94:95], v[90:91], v[94:95] op_sel_hi:[0,1]
	v_pk_mul_f32 v[86:87], v[90:91], v[86:87] op_sel_hi:[0,1]
	v_pk_mul_f32 v[84:85], v[90:91], v[84:85] op_sel_hi:[0,1]
	v_pk_mul_f32 v[82:83], v[90:91], v[82:83] op_sel_hi:[0,1]
	v_pk_mul_f32 v[78:79], v[90:91], v[78:79] op_sel_hi:[0,1]
	v_pk_mul_f32 v[90:91], v[98:99], v[150:151] op_sel_hi:[0,1]
	v_pk_mul_f32 v[100:101], v[98:99], v[100:101] op_sel_hi:[0,1]
	v_pk_mul_f32 v[138:139], v[98:99], v[148:149] op_sel_hi:[0,1]
	v_pk_mul_f32 v[140:141], v[98:99], v[146:147] op_sel_hi:[0,1]
	v_pk_mul_f32 v[130:131], v[98:99], v[130:131] op_sel_hi:[0,1]
	v_pk_mul_f32 v[80:81], v[98:99], v[80:81] op_sel_hi:[0,1]
	v_pk_mul_f32 v[128:129], v[98:99], v[128:129] op_sel_hi:[0,1]
	v_pk_mul_f32 v[98:99], v[98:99], v[126:127] op_sel_hi:[0,1]
	v_pk_mul_f32 v[114:115], v[114:115], v[186:187]
	v_pk_mul_f32 v[92:93], v[92:93], v[182:183]
	v_pk_mul_f32 v[96:97], v[96:97], v[180:181]
	v_pk_mul_f32 v[94:95], v[94:95], v[176:177]
	v_pk_mul_f32 v[86:87], v[86:87], v[124:125]
	v_pk_mul_f32 v[78:79], v[78:79], v[118:119]
	v_pk_mul_f32 v[90:91], v[90:91], v[198:199]
	v_lshlrev_b32_e32 v52, 16, v27
	v_and_b32_e32 v53, 0xffff0000, v27
	v_lshlrev_b32_e32 v56, 16, v26
	v_and_b32_e32 v57, 0xffff0000, v26
	v_pk_mul_f32 v[84:85], v[84:85], v[122:123]
	v_pk_mul_f32 v[82:83], v[82:83], v[120:121]
	v_pk_mul_f32 v[100:101], v[100:101], v[194:195]
	v_pk_mul_f32 v[118:119], v[138:139], v[192:193]
	v_pk_mul_f32 v[120:121], v[140:141], v[188:189]
	v_pk_mul_f32 v[122:123], v[130:131], v[66:67]
	v_pk_mul_f32 v[124:125], v[80:81], v[64:65]
	v_pk_mul_f32 v[126:127], v[128:129], v[62:63]
	v_pk_mul_f32 v[98:99], v[98:99], v[60:61]
	v_cvt_pk_bf16_f32 v60, v114, v115
	v_cvt_pk_bf16_f32 v61, v92, v93
	v_cvt_pk_bf16_f32 v62, v96, v97
	v_cvt_pk_bf16_f32 v63, v94, v95
	v_cvt_pk_bf16_f32 v64, v86, v87
	v_cvt_pk_bf16_f32 v67, v78, v79
	v_cvt_pk_bf16_f32 v78, v90, v91
	v_pk_mul_f32 v[86:87], v[104:105], v[200:201] op_sel_hi:[0,1]
	v_pk_mul_f32 v[90:91], v[104:105], v[112:113] op_sel_hi:[0,1]
	v_pk_mul_f32 v[92:93], v[104:105], v[106:107] op_sel_hi:[0,1]
	v_pk_mul_f32 v[94:95], v[104:105], v[102:103] op_sel_hi:[0,1]
	v_lshlrev_b32_e32 v26, 16, v20
	v_and_b32_e32 v27, 0xffff0000, v20
	v_lshlrev_b32_e32 v20, 16, v21
	v_and_b32_e32 v21, 0xffff0000, v21
	v_cvt_pk_bf16_f32 v65, v84, v85
	v_cvt_pk_bf16_f32 v66, v82, v83
	v_cvt_pk_bf16_f32 v79, v100, v101
	v_cvt_pk_bf16_f32 v80, v118, v119
	v_cvt_pk_bf16_f32 v81, v120, v121
	v_cvt_pk_bf16_f32 v82, v122, v123
	v_cvt_pk_bf16_f32 v83, v124, v125
	v_cvt_pk_bf16_f32 v84, v126, v127
	v_cvt_pk_bf16_f32 v85, v98, v99
	v_pk_mul_f32 v[96:97], v[104:105], v[134:135] op_sel_hi:[0,1]
	v_pk_mul_f32 v[98:99], v[104:105], v[132:133] op_sel_hi:[0,1]
	v_pk_mul_f32 v[72:73], v[104:105], v[72:73] op_sel_hi:[0,1]
	v_pk_mul_f32 v[68:69], v[104:105], v[68:69] op_sel_hi:[0,1]
	v_pk_mul_f32 v[100:101], v[108:109], v[204:205] op_sel_hi:[0,1]
	v_pk_mul_f32 v[102:103], v[108:109], v[116:117] op_sel_hi:[0,1]
	v_pk_mul_f32 v[104:105], v[108:109], v[202:203] op_sel_hi:[0,1]
	v_pk_mul_f32 v[106:107], v[108:109], v[110:111] op_sel_hi:[0,1]
	v_pk_mul_f32 v[110:111], v[108:109], v[136:137] op_sel_hi:[0,1]
	v_pk_mul_f32 v[88:89], v[108:109], v[88:89] op_sel_hi:[0,1]
	v_pk_mul_f32 v[70:71], v[108:109], v[70:71] op_sel_hi:[0,1]
	v_pk_mul_f32 v[22:23], v[108:109], v[22:23] op_sel_hi:[0,1]
	v_mov_b64_e32 v[220:221], v[60:61]
	v_mov_b64_e32 v[222:223], v[62:63]
	v_mov_b64_e32 v[224:225], v[64:65]
	v_mov_b64_e32 v[226:227], v[66:67]
	v_mov_b64_e32 v[228:229], v[78:79]
	v_mov_b64_e32 v[230:231], v[80:81]
	v_mov_b64_e32 v[232:233], v[82:83]
	v_mov_b64_e32 v[234:235], v[84:85]
	v_mov_b64_e32 v[252:253], v[42:43]
	v_pk_mul_f32 v[42:43], v[86:87], v[56:57]
	v_pk_mul_f32 v[52:53], v[90:91], v[52:53]
	v_pk_mul_f32 v[50:51], v[92:93], v[50:51]
	v_pk_mul_f32 v[34:35], v[94:95], v[34:35]
	v_pk_mul_f32 v[46:47], v[96:97], v[46:47]
	v_pk_mul_f32 v[36:37], v[98:99], v[36:37]
	v_pk_mul_f32 v[32:33], v[72:73], v[32:33]
	v_pk_mul_f32 v[30:31], v[68:69], v[30:31]
	v_pk_mul_f32 v[56:57], v[100:101], v[58:59]
	v_pk_mul_f32 v[58:59], v[102:103], v[24:25]
	v_pk_mul_f32 v[54:55], v[104:105], v[54:55]
	v_pk_mul_f32 v[60:61], v[106:107], v[18:19]
	v_pk_mul_f32 v[48:49], v[110:111], v[48:49]
	v_pk_mul_f32 v[62:63], v[88:89], v[28:29]
	v_pk_mul_f32 v[64:65], v[70:71], v[26:27]
	v_pk_mul_f32 v[66:67], v[22:23], v[20:21] op_sel:[1,0] op_sel_hi:[0,1]
	v_cvt_pk_bf16_f32 v18, v42, v43
	v_cvt_pk_bf16_f32 v19, v52, v53
	v_cvt_pk_bf16_f32 v20, v50, v51
	v_cvt_pk_bf16_f32 v21, v34, v35
	v_cvt_pk_bf16_f32 v22, v46, v47
	v_cvt_pk_bf16_f32 v23, v36, v37
	v_cvt_pk_bf16_f32 v24, v32, v33
	v_cvt_pk_bf16_f32 v25, v30, v31
	v_cvt_pk_bf16_f32 v26, v56, v57
	v_cvt_pk_bf16_f32 v27, v58, v59
	v_cvt_pk_bf16_f32 v28, v54, v55
	v_cvt_pk_bf16_f32 v29, v60, v61
	v_cvt_pk_bf16_f32 v30, v48, v49
	v_cvt_pk_bf16_f32 v31, v62, v63
	v_cvt_pk_bf16_f32 v32, v64, v65
	v_cvt_pk_bf16_f32 v33, v66, v67
	s_cmp_lg_u32 s98, 0
	s_cbranch_scc1 .Lg3_last
; #define G3_LOAD(O0, O1, G0, G1_, m) do { O0 = *(const v4u*)(OG + (size_t)(m) * D + 16 * F.lane); O1 = *(const v4u*)(OG + (size_t)(m) * D + 16 * F.lane + 8); \
;             G0 = *(const v4u*)(GR + (size_t)(m) * D + 16 * F.lane); G1_ = *(const v4u*)(GR + (size_t)(m) * D + 16 * F.lane + 8); } while (0)
; template <int K> __device__ __forceinline__ void run_phase(const Args& args, LAS unsigned char* ldsp) {
;     ...
;         const int ms = MP + gw; const bool hasS = ms < M;
;         v4u so0, so1, sg0, sg1;
;         if (hasS) G3_LOAD(so0, so1, sg0, sg1, ms);
;         for (int m0 = 4 * gw; m0 < MP; m0 += 4 * NGW) {
;             v4u ov[4][2], gv4[4][2];
; #pragma unroll
;             for (int r = 0; r < 4; ++r) G3_LOAD(ov[r][0], ov[r][1], gv4[r][0], gv4[r][1], m0 + r);
; #pragma unroll
;             for (int r = 0; r < 4; ++r) G3_DONE(ov[r][0], ov[r][1], gv4[r][0], gv4[r][1], m0 + r);
;         }
;         if (hasS) G3_DONE(so0, so1, sg0, sg1, ms);
;         for (int m = ms + NGW; m < M; m += NGW) { v4u a0, a1, b0, b1; G3_LOAD(a0, a1, b0, b1, m); G3_DONE(a0, a1, b0, b1, m); }
	v_mov_b64_e32 v[236:237], v[18:19]
	v_mov_b64_e32 v[238:239], v[20:21]
	v_mov_b64_e32 v[240:241], v[22:23]
	v_mov_b64_e32 v[242:243], v[24:25]
	v_mov_b64_e32 v[244:245], v[26:27]
	v_mov_b64_e32 v[246:247], v[28:29]
	v_mov_b64_e32 v[248:249], v[30:31]
	v_mov_b64_e32 v[250:251], v[32:33]
	v_add_co_u32_e32 v42, vcc, 0xf3e7f000, v40
	v_lshl_add_u64 v[48:49], v[40:41], 0, s[18:19]
	s_nop 0
	v_addc_co_u32_e32 v43, vcc, -1, v41, vcc
	global_load_dwordx4 v[30:33], v[40:41], off offset:-4096
	global_load_dwordx4 v[34:37], v[40:41], off offset:-2048
	global_load_dwordx4 v[26:29], v[40:41], off offset:-2064
	global_load_dwordx4 v[18:21], v[40:41], off
	global_load_dwordx4 v[22:25], v[40:41], off offset:-16
	v_lshl_add_u64 v[50:51], v[40:41], 0, s[20:21]
	v_lshl_add_u64 v[52:53], v[40:41], 0, s[22:23]
	v_lshl_add_u64 v[46:47], v[40:41], 0, s[24:25]
	global_load_dwordx4 v[68:71], v[48:49], off offset:16
	global_load_dwordx4 v[78:81], v[50:51], off offset:16
	global_load_dwordx4 v[82:85], v[52:53], off offset:16
	v_add_co_u32_e32 v48, vcc, 0xfffff000, v40
	v_lshl_add_u64 v[44:45], v[40:41], 0, s[16:17]
	global_load_dwordx4 v[86:89], v[46:47], off offset:16
	global_load_dwordx4 v[90:93], v[42:43], off offset:-2064
	global_load_dwordx4 v[94:97], v[44:45], off offset:16
	v_addc_co_u32_e32 v49, vcc, -1, v41, vcc
	global_load_dwordx4 v[98:101], v[42:43], off offset:-16
	v_add_co_u32_e32 v44, vcc, s5, v40
	global_load_dwordx4 v[102:105], v[48:49], off offset:-2064
	global_load_dwordx4 v[106:109], v[48:49], off offset:-16
	v_addc_co_u32_e32 v45, vcc, -1, v41, vcc
	global_load_dwordx4 v[110:113], v[44:45], off offset:-2064
	global_load_dwordx4 v[114:117], v[44:45], off offset:-16
	s_add_i32 s10, s10, s12
	s_cmpk_gt_i32 s10, 0x7fff
	v_lshl_add_u64 v[40:41], v[40:41], 0, s[14:15]
	s_cselect_b32 s98, 1, 0
	global_store_dwordx4 v[252:253], v[220:223], off offset:-2064
	global_store_dwordx4 v[252:253], v[224:227], off offset:-2048
	global_store_dwordx4 v[252:253], v[228:231], off offset:-16
	global_store_dwordx4 v[252:253], v[232:235], off
	s_nop 1
	v_lshl_add_u64 v[252:253], v[44:45], 0, s[100:101]
	global_store_dwordx4 v[252:253], v[236:239], off offset:-2064
	global_store_dwordx4 v[252:253], v[240:243], off offset:-2048
	global_store_dwordx4 v[252:253], v[244:247], off offset:-16
	global_store_dwordx4 v[252:253], v[248:251], off
	s_branch .Lg3_loop
.Lg3_last:
	global_store_dwordx4 v[252:253], v[220:223], off offset:-2064
	global_store_dwordx4 v[252:253], v[224:227], off offset:-2048
	global_store_dwordx4 v[252:253], v[228:231], off offset:-16
	global_store_dwordx4 v[252:253], v[232:235], off
	global_store_dwordx4 v[44:45], v[18:21], off offset:-2064
	global_store_dwordx4 v[44:45], v[22:25], off offset:-2048
	global_store_dwordx4 v[44:45], v[26:29], off offset:-16
	global_store_dwordx4 v[44:45], v[30:33], off
